# 7 GEMM K-loop heads aligned to 64 B (s_nop fill) on top of the residual prefetch version
# baseline (speedup 1.0000x reference)
;     __device__ __forceinline__ size_t aoff(const Unit& u, const Gemm& g) const { return (size_t)u.pm * BM * g.K * g.esz; }
;     __device__ __forceinline__ size_t boff(const Unit& u, const Gemm& g) const { return (size_t)u.pn * BM * g.K * g.esz; }
;     __device__ bool next(int i, Unit& u) const { const int L = i * G + c; if (L >= 256) return false; u.g = L >> 6; const int r = L & 63; u.pm = r >> 1; u.pn = r & 1; return true; }
;     __device__ __forceinline__ size_t aoff(const Unit& u, const Gemm& g) const { return (size_t)(u.g * 32 + u.pm) * BM * g.K * g.esz; }
;     __device__ __forceinline__ size_t boff(const Unit& u, const Gemm& g) const { return (size_t)(u.g * 2 + u.pn) * BM * g.K * g.esz; }
; template <class Epi, class Sched, bool I8 = false>
; __device__ __forceinline__ void gemm_phase(LAS unsigned char* lds, const Gemm g, const Sched& S, const Epi& E) {
;     ...
;     for (;;) {
;         const bool has_next = S.next(ui + 1, nxt);
;         const char* nA = has_next ? (const char*)g.A + S.aoff(nxt, g) : cA; const char* nB = has_next ? (const char*)g.Bt + S.boff(nxt, g) : cB;
;         for (int t = 0; t < nt; t += 2) {
;             const bool last = (t == nt - 2);
;             const char* a1 = cA + (size_t)(t + 1) * kstep;
;             const char* a2 = last ? nA : cA + (size_t)(t + 2) * kstep; const char* b2 = last ? nB : cB + (size_t)(t + 2) * kstep;
;             const char* a3 = a2 + kstep; const char* b3 = b2 + kstep;
;     ...
; #pragma unroll
;         for (int a = 0; a < 2; ++a)
; #pragma unroll
;             for (int b = 0; b < 2; ++b)
; #pragma unroll
;                 for (int m = 0; m < 4; ++m)
; #pragma unroll
;                     for (int n = 0; n < 2; ++n) acc[a][b][m][n] = acc_t{};
;         cur = nxt; cA = nA; cB = nB; ++ui;
.LBB0_1168:
	s_ashr_i32 s13, s12, 31
	s_lshl_b64 s[14:15], s[12:13], 20
	s_add_u32 s14, s28, s14
	s_addc_u32 s15, s29, s15
	s_and_b64 s[16:17], s[2:3], exec
	s_cselect_b32 s13, s15, s21
	s_cselect_b32 s49, s14, s20
	s_ashr_i32 s11, s10, 31
	s_lshl_b64 s[16:17], s[10:11], 20
	s_add_u32 s16, s30, s16
	s_addc_u32 s17, s31, s17
	s_and_b64 s[24:25], s[2:3], exec
	s_cselect_b32 s11, s17, s23
	s_cselect_b32 s50, s16, s22
	s_add_u32 s20, s20, 0xc000
	s_addc_u32 s21, s21, 0
	s_add_u32 s51, s22, 0x10000
	v_mov_b32_e32 v2, 0
	s_addc_u32 s52, s23, 0
	s_mov_b32 s53, -2
	v_mov_b32_e32 v3, v2
	v_mov_b32_e32 v4, v2
	v_mov_b32_e32 v5, v2
	v_mov_b32_e32 v6, v2
	v_mov_b32_e32 v7, v2
	v_mov_b32_e32 v8, v2
	v_mov_b32_e32 v9, v2
	v_mov_b32_e32 v18, v2
	v_mov_b32_e32 v19, v2
	v_mov_b32_e32 v20, v2
	v_mov_b32_e32 v21, v2
	v_mov_b32_e32 v22, v2
	v_mov_b32_e32 v23, v2
	v_mov_b32_e32 v24, v2
	v_mov_b32_e32 v25, v2
	v_mov_b32_e32 v34, v2
	v_mov_b32_e32 v35, v2
	v_mov_b32_e32 v36, v2
	v_mov_b32_e32 v37, v2
	v_mov_b32_e32 v38, v2
	v_mov_b32_e32 v39, v2
	v_mov_b32_e32 v40, v2
	v_mov_b32_e32 v41, v2
	v_mov_b32_e32 v50, v2
	v_mov_b32_e32 v51, v2
	v_mov_b32_e32 v52, v2
	v_mov_b32_e32 v53, v2
	v_mov_b32_e32 v54, v2
	v_mov_b32_e32 v55, v2
	v_mov_b32_e32 v56, v2
	v_mov_b32_e32 v57, v2
	v_mov_b32_e32 v10, v2
	v_mov_b32_e32 v11, v2
	v_mov_b32_e32 v12, v2
	v_mov_b32_e32 v13, v2
	v_mov_b32_e32 v14, v2
	v_mov_b32_e32 v15, v2
	v_mov_b32_e32 v16, v2
	v_mov_b32_e32 v17, v2
	v_mov_b32_e32 v26, v2
	v_mov_b32_e32 v27, v2
	v_mov_b32_e32 v28, v2
	v_mov_b32_e32 v29, v2
	v_mov_b32_e32 v30, v2
	v_mov_b32_e32 v31, v2
	v_mov_b32_e32 v32, v2
	v_mov_b32_e32 v33, v2
	v_mov_b32_e32 v42, v2
	v_mov_b32_e32 v43, v2
	v_mov_b32_e32 v44, v2
	v_mov_b32_e32 v45, v2
	v_mov_b32_e32 v46, v2
	v_mov_b32_e32 v47, v2
	v_mov_b32_e32 v48, v2
	v_mov_b32_e32 v49, v2
	v_mov_b32_e32 v58, v2
	v_mov_b32_e32 v59, v2
	v_mov_b32_e32 v60, v2
	v_mov_b32_e32 v61, v2
	v_mov_b32_e32 v62, v2
	v_mov_b32_e32 v63, v2
	v_mov_b32_e32 v64, v2
	v_mov_b32_e32 v65, v2
	v_mov_b32_e32 v66, v2
	v_mov_b32_e32 v67, v2
	v_mov_b32_e32 v68, v2
	v_mov_b32_e32 v69, v2
	v_mov_b32_e32 v70, v2
	v_mov_b32_e32 v71, v2
	v_mov_b32_e32 v72, v2
	v_mov_b32_e32 v73, v2
	v_mov_b32_e32 v82, v2
	v_mov_b32_e32 v83, v2
	v_mov_b32_e32 v84, v2
	v_mov_b32_e32 v85, v2
	v_mov_b32_e32 v86, v2
	v_mov_b32_e32 v87, v2
	v_mov_b32_e32 v88, v2
	v_mov_b32_e32 v89, v2
	v_mov_b32_e32 v106, v2
	v_mov_b32_e32 v107, v2
	v_mov_b32_e32 v108, v2
	v_mov_b32_e32 v109, v2
	v_mov_b32_e32 v110, v2
	v_mov_b32_e32 v111, v2
	v_mov_b32_e32 v112, v2
	v_mov_b32_e32 v113, v2
	v_mov_b32_e32 v122, v2
	v_mov_b32_e32 v123, v2
	v_mov_b32_e32 v124, v2
	v_mov_b32_e32 v125, v2
	v_mov_b32_e32 v126, v2
	v_mov_b32_e32 v127, v2
	v_mov_b32_e32 v128, v2
	v_mov_b32_e32 v129, v2
	v_mov_b32_e32 v74, v2
	v_mov_b32_e32 v75, v2
	v_mov_b32_e32 v76, v2
	v_mov_b32_e32 v77, v2
	v_mov_b32_e32 v78, v2
	v_mov_b32_e32 v79, v2
	v_mov_b32_e32 v80, v2
	v_mov_b32_e32 v81, v2
	v_mov_b32_e32 v94, v2
	v_mov_b32_e32 v95, v2
	v_mov_b32_e32 v96, v2
	v_mov_b32_e32 v97, v2
	v_mov_b32_e32 v102, v2
	v_mov_b32_e32 v103, v2
	v_mov_b32_e32 v104, v2
	v_mov_b32_e32 v105, v2
	v_mov_b32_e32 v114, v2
	v_mov_b32_e32 v115, v2
	v_mov_b32_e32 v116, v2
	v_mov_b32_e32 v117, v2
	v_mov_b32_e32 v118, v2
	v_mov_b32_e32 v119, v2
	v_mov_b32_e32 v120, v2
	v_mov_b32_e32 v121, v2
	v_mov_b32_e32 v130, v2
	v_mov_b32_e32 v131, v2
	v_mov_b32_e32 v132, v2
	v_mov_b32_e32 v133, v2
	v_mov_b32_e32 v134, v2
	v_mov_b32_e32 v135, v2
	v_mov_b32_e32 v136, v2
	v_mov_b32_e32 v137, v2
	.p2alignl 6, 3212836864

; template <class Epi, class Sched, bool I8 = false>
; __device__ __forceinline__ void gemm_phase(LAS unsigned char* lds, const Gemm g, const Sched& S, const Epi& E) {
;     ...
;         for (int t = 0; t < nt; t += 2) {
;             const bool last = (t == nt - 2);
;             const char* a1 = cA + (size_t)(t + 1) * kstep;
;             const char* a2 = last ? nA : cA + (size_t)(t + 2) * kstep; const char* b2 = last ? nB : cB + (size_t)(t + 2) * kstep;
;             const char* a3 = a2 + kstep; const char* b3 = b2 + kstep;
;     __device__ __forceinline__ void operator()(const i32x4 (&acc)[2][2][4][2], const pg8::Unit& u, int wr, int wc, int fr, int fq) const {
;     ...
;             for (int mh = 0; mh < 2; ++mh) {
;                 f32x4 pa[2][2], pb[2][2]; float rs[2];
; #pragma unroll
;                 for (int mm = 0; mm < 2; ++mm) { const int row = row0 + ai * 128 + (2 * mh + mm) * 16; rs[mm] = sh[row] * alpha;
; #pragma unroll
;                     for (int bj = 0; bj < 2; ++bj) { const size_t off = (size_t)row * DM + col0 + bj * 128; pa[mm][bj] = *(const f32x4*)(res + off); pb[mm][bj] = *(const f32x4*)(res + off + 4); } }
.LBB0_1392:
	s_add_u32 s18, s18, 0xc000
	s_addc_u32 s19, s19, 0
	s_add_u32 s47, s20, 0x10000
	v_mov_b32_e32 v2, 0
	s_addc_u32 s48, s21, 0
	s_mov_b32 s49, -2
	s_waitcnt lgkmcnt(0)
	v_mov_b32_e32 v3, v2
	v_mov_b32_e32 v4, v2
	v_mov_b32_e32 v5, v2
	v_mov_b32_e32 v6, v2
	v_mov_b32_e32 v7, v2
	v_mov_b32_e32 v8, v2
	v_mov_b32_e32 v9, v2
	v_mov_b32_e32 v18, v2
	v_mov_b32_e32 v19, v2
	v_mov_b32_e32 v20, v2
	v_mov_b32_e32 v21, v2
	v_mov_b32_e32 v22, v2
	v_mov_b32_e32 v23, v2
	v_mov_b32_e32 v24, v2
	v_mov_b32_e32 v25, v2
	v_mov_b32_e32 v34, v2
	v_mov_b32_e32 v35, v2
	v_mov_b32_e32 v36, v2
	v_mov_b32_e32 v37, v2
	v_mov_b32_e32 v38, v2
	v_mov_b32_e32 v39, v2
	v_mov_b32_e32 v40, v2
	v_mov_b32_e32 v41, v2
	v_mov_b32_e32 v50, v2
	v_mov_b32_e32 v51, v2
	v_mov_b32_e32 v52, v2
	v_mov_b32_e32 v53, v2
	v_mov_b32_e32 v54, v2
	v_mov_b32_e32 v55, v2
	v_mov_b32_e32 v56, v2
	v_mov_b32_e32 v57, v2
	v_mov_b32_e32 v10, v2
	v_mov_b32_e32 v11, v2
	v_mov_b32_e32 v12, v2
	v_mov_b32_e32 v13, v2
	v_mov_b32_e32 v14, v2
	v_mov_b32_e32 v15, v2
	v_mov_b32_e32 v16, v2
	v_mov_b32_e32 v17, v2
	v_mov_b32_e32 v26, v2
	v_mov_b32_e32 v27, v2
	v_mov_b32_e32 v28, v2
	v_mov_b32_e32 v29, v2
	v_mov_b32_e32 v30, v2
	v_mov_b32_e32 v31, v2
	v_mov_b32_e32 v32, v2
	v_mov_b32_e32 v33, v2
	v_mov_b32_e32 v42, v2
	v_mov_b32_e32 v43, v2
	v_mov_b32_e32 v44, v2
	v_mov_b32_e32 v45, v2
	v_mov_b32_e32 v46, v2
	v_mov_b32_e32 v47, v2
	v_mov_b32_e32 v48, v2
	v_mov_b32_e32 v49, v2
	v_mov_b32_e32 v58, v2
	v_mov_b32_e32 v59, v2
	v_mov_b32_e32 v60, v2
	v_mov_b32_e32 v61, v2
	v_mov_b32_e32 v62, v2
	v_mov_b32_e32 v63, v2
	v_mov_b32_e32 v64, v2
	v_mov_b32_e32 v65, v2
	v_mov_b32_e32 v82, v2
	v_mov_b32_e32 v83, v2
	v_mov_b32_e32 v84, v2
	v_mov_b32_e32 v85, v2
	v_mov_b32_e32 v86, v2
	v_mov_b32_e32 v87, v2
	v_mov_b32_e32 v88, v2
	v_mov_b32_e32 v89, v2
	v_mov_b32_e32 v98, v2
	v_mov_b32_e32 v99, v2
	v_mov_b32_e32 v100, v2
	v_mov_b32_e32 v101, v2
	v_mov_b32_e32 v102, v2
	v_mov_b32_e32 v103, v2
	v_mov_b32_e32 v104, v2
	v_mov_b32_e32 v105, v2
	v_mov_b32_e32 v114, v2
	v_mov_b32_e32 v115, v2
	v_mov_b32_e32 v116, v2
	v_mov_b32_e32 v117, v2
	v_mov_b32_e32 v118, v2
	v_mov_b32_e32 v119, v2
	v_mov_b32_e32 v120, v2
	v_mov_b32_e32 v121, v2
	v_mov_b32_e32 v130, v2
	v_mov_b32_e32 v131, v2
	v_mov_b32_e32 v132, v2
	v_mov_b32_e32 v133, v2
	v_mov_b32_e32 v134, v2
	v_mov_b32_e32 v135, v2
	v_mov_b32_e32 v136, v2
	v_mov_b32_e32 v137, v2
	v_mov_b32_e32 v90, v2
	v_mov_b32_e32 v91, v2
	v_mov_b32_e32 v92, v2
	v_mov_b32_e32 v93, v2
	v_mov_b32_e32 v94, v2
	v_mov_b32_e32 v95, v2
	v_mov_b32_e32 v96, v2
	v_mov_b32_e32 v97, v2
	v_mov_b32_e32 v106, v2
	v_mov_b32_e32 v107, v2
	v_mov_b32_e32 v108, v2
	v_mov_b32_e32 v109, v2
	v_mov_b32_e32 v110, v2
	v_mov_b32_e32 v111, v2
	v_mov_b32_e32 v112, v2
	v_mov_b32_e32 v113, v2
	v_mov_b32_e32 v122, v2
	v_mov_b32_e32 v123, v2
	v_mov_b32_e32 v124, v2
	v_mov_b32_e32 v125, v2
	v_mov_b32_e32 v126, v2
	v_mov_b32_e32 v127, v2
	v_mov_b32_e32 v128, v2
	v_mov_b32_e32 v129, v2
	v_mov_b32_e32 v138, v2
	v_mov_b32_e32 v139, v2
	v_mov_b32_e32 v140, v2
	v_mov_b32_e32 v141, v2
	v_mov_b32_e32 v142, v2
	v_mov_b32_e32 v143, v2
	v_mov_b32_e32 v144, v2
	v_mov_b32_e32 v145, v2
	v_lshl_add_u32 v252, s45, 8, v1
	v_lshl_or_b32 v253, s46, 8, v179
	v_lshlrev_b32_e32 v252, 14, v252
	v_lshl_add_u32 v252, v253, 2, v252
	v_mov_b32_e32 v253, 0
	v_lshl_add_u64 v[252:253], v[252:253], 0, v[154:155]
	v_mov_b32_e32 v248, 0x40000
	v_mov_b32_e32 v249, 0
	v_lshl_add_u64 v[248:249], v[248:249], 0, v[252:253]
	global_load_dwordx4 v[222:225], v[252:253], off nt
	global_load_dwordx4 v[226:229], v[252:253], off offset:16 nt
	global_load_dwordx4 v[230:233], v[252:253], off offset:512 nt
	global_load_dwordx4 v[234:237], v[248:249], off offset:16 nt
	global_load_dwordx4 v[238:241], v[248:249], off nt
	global_load_dwordx4 v[242:245], v[248:249], off offset:528 nt
	s_nop 0
	global_load_dwordx4 v[252:255], v[252:253], off offset:528 nt
	s_nop 0
	global_load_dwordx4 v[248:251], v[248:249], off offset:512 nt
	.p2alignl 6, 3212836864

;     __device__ __forceinline__ size_t aoff(const Unit& u, const Gemm& g) const { return (size_t)u.pm * BM * g.K * g.esz; }
;     __device__ __forceinline__ size_t boff(const Unit& u, const Gemm& g) const { return (size_t)u.pn * BM * g.K * g.esz; }
;     __device__ bool next(int i, Unit& u) const { const int L = i * G + c; if (L >= 256) return false; u.g = L >> 6; const int r = L & 63; u.pm = r >> 1; u.pn = r & 1; return true; }
;     __device__ __forceinline__ size_t aoff(const Unit& u, const Gemm& g) const { return (size_t)(u.g * 32 + u.pm) * BM * g.K * g.esz; }
;     __device__ __forceinline__ size_t boff(const Unit& u, const Gemm& g) const { return (size_t)(u.g * 2 + u.pn) * BM * g.K * g.esz; }
; template <class Epi, class Sched, bool I8 = false>
; __device__ __forceinline__ void gemm_phase(LAS unsigned char* lds, const Gemm g, const Sched& S, const Epi& E) {
;     ...
;     for (;;) {
;         const bool has_next = S.next(ui + 1, nxt);
;         const char* nA = has_next ? (const char*)g.A + S.aoff(nxt, g) : cA; const char* nB = has_next ? (const char*)g.Bt + S.boff(nxt, g) : cB;
;         for (int t = 0; t < nt; t += 2) {
;             const bool last = (t == nt - 2);
;             const char* a1 = cA + (size_t)(t + 1) * kstep;
;             const char* a2 = last ? nA : cA + (size_t)(t + 2) * kstep; const char* b2 = last ? nB : cB + (size_t)(t + 2) * kstep;
;             const char* a3 = a2 + kstep; const char* b3 = b2 + kstep;
;     ...
; #pragma unroll
;         for (int a = 0; a < 2; ++a)
; #pragma unroll
;             for (int b = 0; b < 2; ++b)
; #pragma unroll
;                 for (int m = 0; m < 4; ++m)
; #pragma unroll
;                     for (int n = 0; n < 2; ++n) acc[a][b][m][n] = acc_t{};
;         cur = nxt; cA = nA; cB = nB; ++ui;
.LBB0_1481:
	s_ashr_i32 s31, s30, 31
	s_lshl_b64 s[34:35], s[30:31], 21
	s_add_u32 s34, s72, s34
	s_addc_u32 s35, s73, s35
	s_and_b64 s[36:37], s[4:5], exec
	s_cselect_b32 s7, s35, s9
	s_cselect_b32 s31, s34, s8
	s_ashr_i32 s29, s28, 31
	s_lshl_b64 s[36:37], s[28:29], 21
	s_add_u32 s36, s10, s36
	s_addc_u32 s37, s11, s37
	s_and_b64 s[40:41], s[4:5], exec
	s_cselect_b32 s29, s37, s39
	s_cselect_b32 s44, s36, s38
	s_add_u32 s8, s8, 0xc000
	s_addc_u32 s9, s9, 0
	s_add_u32 s45, s38, 0x10000
	v_mov_b32_e32 v2, 0
	s_addc_u32 s46, s39, 0
	s_mov_b32 s47, -2
	v_mov_b32_e32 v3, v2
	v_mov_b32_e32 v4, v2
	v_mov_b32_e32 v5, v2
	v_mov_b32_e32 v6, v2
	v_mov_b32_e32 v7, v2
	v_mov_b32_e32 v8, v2
	v_mov_b32_e32 v9, v2
	v_mov_b32_e32 v18, v2
	v_mov_b32_e32 v19, v2
	v_mov_b32_e32 v20, v2
	v_mov_b32_e32 v21, v2
	v_mov_b32_e32 v22, v2
	v_mov_b32_e32 v23, v2
	v_mov_b32_e32 v24, v2
	v_mov_b32_e32 v25, v2
	v_mov_b32_e32 v34, v2
	v_mov_b32_e32 v35, v2
	v_mov_b32_e32 v36, v2
	v_mov_b32_e32 v37, v2
	v_mov_b32_e32 v38, v2
	v_mov_b32_e32 v39, v2
	v_mov_b32_e32 v40, v2
	v_mov_b32_e32 v41, v2
	v_mov_b32_e32 v50, v2
	v_mov_b32_e32 v51, v2
	v_mov_b32_e32 v52, v2
	v_mov_b32_e32 v53, v2
	v_mov_b32_e32 v54, v2
	v_mov_b32_e32 v55, v2
	v_mov_b32_e32 v56, v2
	v_mov_b32_e32 v57, v2
	v_mov_b32_e32 v10, v2
	v_mov_b32_e32 v11, v2
	v_mov_b32_e32 v12, v2
	v_mov_b32_e32 v13, v2
	v_mov_b32_e32 v14, v2
	v_mov_b32_e32 v15, v2
	v_mov_b32_e32 v16, v2
	v_mov_b32_e32 v17, v2
	v_mov_b32_e32 v26, v2
	v_mov_b32_e32 v27, v2
	v_mov_b32_e32 v28, v2
	v_mov_b32_e32 v29, v2
	v_mov_b32_e32 v30, v2
	v_mov_b32_e32 v31, v2
	v_mov_b32_e32 v32, v2
	v_mov_b32_e32 v33, v2
	v_mov_b32_e32 v42, v2
	v_mov_b32_e32 v43, v2
	v_mov_b32_e32 v44, v2
	v_mov_b32_e32 v45, v2
	v_mov_b32_e32 v46, v2
	v_mov_b32_e32 v47, v2
	v_mov_b32_e32 v48, v2
	v_mov_b32_e32 v49, v2
	v_mov_b32_e32 v58, v2
	v_mov_b32_e32 v59, v2
	v_mov_b32_e32 v60, v2
	v_mov_b32_e32 v61, v2
	v_mov_b32_e32 v62, v2
	v_mov_b32_e32 v63, v2
	v_mov_b32_e32 v64, v2
	v_mov_b32_e32 v65, v2
	v_mov_b32_e32 v66, v2
	v_mov_b32_e32 v67, v2
	v_mov_b32_e32 v68, v2
	v_mov_b32_e32 v69, v2
	v_mov_b32_e32 v70, v2
	v_mov_b32_e32 v71, v2
	v_mov_b32_e32 v72, v2
	v_mov_b32_e32 v73, v2
	v_mov_b32_e32 v82, v2
	v_mov_b32_e32 v83, v2
	v_mov_b32_e32 v84, v2
	v_mov_b32_e32 v85, v2
	v_mov_b32_e32 v86, v2
	v_mov_b32_e32 v87, v2
	v_mov_b32_e32 v88, v2
	v_mov_b32_e32 v89, v2
	v_mov_b32_e32 v98, v2
	v_mov_b32_e32 v99, v2
	v_mov_b32_e32 v100, v2
	v_mov_b32_e32 v101, v2
	v_mov_b32_e32 v102, v2
	v_mov_b32_e32 v103, v2
	v_mov_b32_e32 v104, v2
	v_mov_b32_e32 v105, v2
	v_mov_b32_e32 v114, v2
	v_mov_b32_e32 v115, v2
	v_mov_b32_e32 v116, v2
	v_mov_b32_e32 v117, v2
	v_mov_b32_e32 v118, v2
	v_mov_b32_e32 v119, v2
	v_mov_b32_e32 v120, v2
	v_mov_b32_e32 v121, v2
	v_mov_b32_e32 v74, v2
	v_mov_b32_e32 v75, v2
	v_mov_b32_e32 v76, v2
	v_mov_b32_e32 v77, v2
	v_mov_b32_e32 v78, v2
	v_mov_b32_e32 v79, v2
	v_mov_b32_e32 v80, v2
	v_mov_b32_e32 v81, v2
	v_mov_b32_e32 v90, v2
	v_mov_b32_e32 v91, v2
	v_mov_b32_e32 v92, v2
	v_mov_b32_e32 v93, v2
	v_mov_b32_e32 v94, v2
	v_mov_b32_e32 v95, v2
	v_mov_b32_e32 v96, v2
	v_mov_b32_e32 v97, v2
	v_mov_b32_e32 v106, v2
	v_mov_b32_e32 v107, v2
	v_mov_b32_e32 v108, v2
	v_mov_b32_e32 v109, v2
	v_mov_b32_e32 v110, v2
	v_mov_b32_e32 v111, v2
	v_mov_b32_e32 v112, v2
	v_mov_b32_e32 v113, v2
	v_mov_b32_e32 v122, v2
	v_mov_b32_e32 v123, v2
	v_mov_b32_e32 v124, v2
	v_mov_b32_e32 v125, v2
	v_mov_b32_e32 v126, v2
	v_mov_b32_e32 v127, v2
	v_mov_b32_e32 v128, v2
	v_mov_b32_e32 v129, v2
	.p2alignl 6, 3212836864

;     __device__ __forceinline__ size_t aoff(const Unit& u, const Gemm& g) const { return (size_t)u.pm * BM * g.K * g.esz; }
;     __device__ __forceinline__ size_t boff(const Unit& u, const Gemm& g) const { return (size_t)u.pn * BM * g.K * g.esz; }
;     __device__ bool next(int i, Unit& u) const { const int L = i * G + c; if (L >= 256) return false; u.g = L >> 6; const int r = L & 63; u.pm = r >> 1; u.pn = r & 1; return true; }
;     __device__ __forceinline__ size_t aoff(const Unit& u, const Gemm& g) const { return (size_t)(u.g * 32 + u.pm) * BM * g.K * g.esz; }
;     __device__ __forceinline__ size_t boff(const Unit& u, const Gemm& g) const { return (size_t)(u.g * 2 + u.pn) * BM * g.K * g.esz; }
; template <class Epi, class Sched, bool I8 = false>
; __device__ __forceinline__ void gemm_phase(LAS unsigned char* lds, const Gemm g, const Sched& S, const Epi& E) {
;     ...
;     for (;;) {
;         const bool has_next = S.next(ui + 1, nxt);
;         const char* nA = has_next ? (const char*)g.A + S.aoff(nxt, g) : cA; const char* nB = has_next ? (const char*)g.Bt + S.boff(nxt, g) : cB;
;         for (int t = 0; t < nt; t += 2) {
;             const bool last = (t == nt - 2);
;             const char* a1 = cA + (size_t)(t + 1) * kstep;
;             const char* a2 = last ? nA : cA + (size_t)(t + 2) * kstep; const char* b2 = last ? nB : cB + (size_t)(t + 2) * kstep;
;             const char* a3 = a2 + kstep; const char* b3 = b2 + kstep;
.LBB0_2684:
	s_add_i32 s30, s30, 1
	s_mov_b64 s[12:13], s[0:1]
	s_mul_i32 s0, s30, s71
	s_add_i32 s0, s0, s74
	s_cmpk_lt_i32 s0, 0x100
	s_mov_b32 s38, s24
	s_cselect_b64 s[8:9], -1, 0
	s_ashr_i32 s24, s0, 6
	s_mov_b32 s36, s25
	s_mov_b32 s37, s23
	s_and_b32 s23, s0, 1
	s_bfe_u32 s25, s0, 0x50001
	s_lshl_b32 s0, s24, 5
	s_or_b32 s0, s0, s25
	s_ashr_i32 s1, s0, 31
	s_lshl_b64 s[0:1], s[0:1], 18
	s_mov_b64 s[10:11], s[2:3]
	s_add_u32 s2, s18, s0
	s_addc_u32 s3, s19, s1
	s_and_b64 s[0:1], s[8:9], exec
	s_cselect_b32 s39, s3, s11
	s_cselect_b32 s40, s2, s10
	s_lshl_b32 s0, s24, 1
	s_or_b32 s0, s0, s23
	s_ashr_i32 s1, s0, 31
	s_lshl_b64 s[0:1], s[0:1], 18
	s_add_u32 s0, s20, s0
	s_addc_u32 s1, s21, s1
	s_and_b64 s[14:15], s[8:9], exec
	s_cselect_b32 s41, s1, s13
	s_cselect_b32 s42, s0, s12
	s_add_u32 s10, s10, 0xc000
	s_addc_u32 s11, s11, 0
	s_add_u32 s43, s12, 0x10000
	v_mov_b32_e32 v2, 0
	s_addc_u32 s44, s13, 0
	s_mov_b32 s45, -2
	v_mov_b32_e32 v3, v2
	v_mov_b32_e32 v4, v2
	v_mov_b32_e32 v5, v2
	v_mov_b32_e32 v6, v2
	v_mov_b32_e32 v7, v2
	v_mov_b32_e32 v8, v2
	v_mov_b32_e32 v9, v2
	v_mov_b32_e32 v10, v2
	v_mov_b32_e32 v11, v2
	v_mov_b32_e32 v12, v2
	v_mov_b32_e32 v13, v2
	v_mov_b32_e32 v14, v2
	v_mov_b32_e32 v15, v2
	v_mov_b32_e32 v16, v2
	v_mov_b32_e32 v17, v2
	v_mov_b32_e32 v18, v2
	v_mov_b32_e32 v19, v2
	v_mov_b32_e32 v20, v2
	v_mov_b32_e32 v21, v2
	v_mov_b32_e32 v22, v2
	v_mov_b32_e32 v23, v2
	v_mov_b32_e32 v24, v2
	v_mov_b32_e32 v25, v2
	v_mov_b32_e32 v26, v2
	v_mov_b32_e32 v27, v2
	v_mov_b32_e32 v28, v2
	v_mov_b32_e32 v29, v2
	v_mov_b32_e32 v30, v2
	v_mov_b32_e32 v31, v2
	v_mov_b32_e32 v32, v2
	v_mov_b32_e32 v33, v2
	v_mov_b32_e32 v66, v2
	v_mov_b32_e32 v67, v2
	v_mov_b32_e32 v68, v2
	v_mov_b32_e32 v69, v2
	v_mov_b32_e32 v70, v2
	v_mov_b32_e32 v71, v2
	v_mov_b32_e32 v72, v2
	v_mov_b32_e32 v73, v2
	v_mov_b32_e32 v74, v2
	v_mov_b32_e32 v75, v2
	v_mov_b32_e32 v76, v2
	v_mov_b32_e32 v77, v2
	v_mov_b32_e32 v78, v2
	v_mov_b32_e32 v79, v2
	v_mov_b32_e32 v80, v2
	v_mov_b32_e32 v81, v2
	v_mov_b32_e32 v82, v2
	v_mov_b32_e32 v83, v2
	v_mov_b32_e32 v84, v2
	v_mov_b32_e32 v85, v2
	v_mov_b32_e32 v86, v2
	v_mov_b32_e32 v87, v2
	v_mov_b32_e32 v88, v2
	v_mov_b32_e32 v89, v2
	v_mov_b32_e32 v90, v2
	v_mov_b32_e32 v91, v2
	v_mov_b32_e32 v92, v2
	v_mov_b32_e32 v93, v2
	v_mov_b32_e32 v94, v2
	v_mov_b32_e32 v95, v2
	v_mov_b32_e32 v96, v2
	v_mov_b32_e32 v97, v2
	v_mov_b32_e32 v34, v2
	v_mov_b32_e32 v35, v2
	v_mov_b32_e32 v36, v2
	v_mov_b32_e32 v37, v2
	v_mov_b32_e32 v38, v2
	v_mov_b32_e32 v39, v2
	v_mov_b32_e32 v40, v2
	v_mov_b32_e32 v41, v2
	v_mov_b32_e32 v42, v2
	v_mov_b32_e32 v43, v2
	v_mov_b32_e32 v44, v2
	v_mov_b32_e32 v45, v2
	v_mov_b32_e32 v46, v2
	v_mov_b32_e32 v47, v2
	v_mov_b32_e32 v48, v2
	v_mov_b32_e32 v49, v2
	v_mov_b32_e32 v50, v2
	v_mov_b32_e32 v51, v2
	v_mov_b32_e32 v52, v2
	v_mov_b32_e32 v53, v2
	v_mov_b32_e32 v54, v2
	v_mov_b32_e32 v55, v2
	v_mov_b32_e32 v56, v2
	v_mov_b32_e32 v57, v2
	v_mov_b32_e32 v58, v2
	v_mov_b32_e32 v59, v2
	v_mov_b32_e32 v60, v2
	v_mov_b32_e32 v61, v2
	v_mov_b32_e32 v62, v2
	v_mov_b32_e32 v63, v2
	v_mov_b32_e32 v64, v2
	v_mov_b32_e32 v65, v2
	v_mov_b32_e32 v98, v2
	v_mov_b32_e32 v99, v2
	v_mov_b32_e32 v100, v2
	v_mov_b32_e32 v101, v2
	v_mov_b32_e32 v102, v2
	v_mov_b32_e32 v103, v2
	v_mov_b32_e32 v104, v2
	v_mov_b32_e32 v105, v2
	v_mov_b32_e32 v106, v2
	v_mov_b32_e32 v107, v2
	v_mov_b32_e32 v108, v2
	v_mov_b32_e32 v109, v2
	v_mov_b32_e32 v110, v2
	v_mov_b32_e32 v111, v2
	v_mov_b32_e32 v112, v2
	v_mov_b32_e32 v113, v2
	v_mov_b32_e32 v114, v2
	v_mov_b32_e32 v115, v2
	v_mov_b32_e32 v116, v2
	v_mov_b32_e32 v117, v2
	v_mov_b32_e32 v118, v2
	v_mov_b32_e32 v119, v2
	v_mov_b32_e32 v120, v2
	v_mov_b32_e32 v121, v2
	v_mov_b32_e32 v122, v2
	v_mov_b32_e32 v123, v2
	v_mov_b32_e32 v124, v2
	v_mov_b32_e32 v125, v2
	v_mov_b32_e32 v126, v2
	v_mov_b32_e32 v127, v2
	v_mov_b32_e32 v128, v2
	v_mov_b32_e32 v129, v2
	.p2alignl 6, 3212836864

;     __device__ __forceinline__ size_t aoff(const Unit& u, const Gemm& g) const { return (size_t)u.pm * BM * g.K * g.esz; }
;     __device__ __forceinline__ size_t boff(const Unit& u, const Gemm& g) const { return (size_t)u.pn * BM * g.K * g.esz; }
;     __device__ bool next(int i, Unit& u) const { const int L = i * G + c; if (L >= 256) return false; u.g = L >> 6; const int r = L & 63; u.pm = r >> 1; u.pn = r & 1; return true; }
;     __device__ __forceinline__ size_t aoff(const Unit& u, const Gemm& g) const { return (size_t)(u.g * 32 + u.pm) * BM * g.K * g.esz; }
;     __device__ __forceinline__ size_t boff(const Unit& u, const Gemm& g) const { return (size_t)(u.g * 2 + u.pn) * BM * g.K * g.esz; }
; template <class Epi, class Sched, bool I8 = false>
; __device__ __forceinline__ void gemm_phase(LAS unsigned char* lds, const Gemm g, const Sched& S, const Epi& E) {
;     ...
;     for (;;) {
;         const bool has_next = S.next(ui + 1, nxt);
;         const char* nA = has_next ? (const char*)g.A + S.aoff(nxt, g) : cA; const char* nB = has_next ? (const char*)g.Bt + S.boff(nxt, g) : cB;
;         for (int t = 0; t < nt; t += 2) {
;             const bool last = (t == nt - 2);
;             const char* a1 = cA + (size_t)(t + 1) * kstep;
;             const char* a2 = last ? nA : cA + (size_t)(t + 2) * kstep; const char* b2 = last ? nB : cB + (size_t)(t + 2) * kstep;
;             const char* a3 = a2 + kstep; const char* b3 = b2 + kstep;
;     ...
; #pragma unroll
;         for (int a = 0; a < 2; ++a)
; #pragma unroll
;             for (int b = 0; b < 2; ++b)
; #pragma unroll
;                 for (int m = 0; m < 4; ++m)
; #pragma unroll
;                     for (int n = 0; n < 2; ++n) acc[a][b][m][n] = acc_t{};
;         cur = nxt; cA = nA; cB = nB; ++ui;
.LBB0_3743:
	s_ashr_i32 s23, s22, 31
	s_lshl_b64 s[24:25], s[22:23], 21
	s_add_u32 s24, s33, s24
	s_addc_u32 s25, s40, s25
	s_and_b64 s[26:27], s[2:3], exec
	s_cselect_b32 s5, s25, s31
	s_cselect_b32 s23, s24, s30
	s_ashr_i32 s21, s20, 31
	s_lshl_b64 s[26:27], s[20:21], 21
	s_add_u32 s26, s41, s26
	s_addc_u32 s27, s42, s27
	s_and_b64 s[36:37], s[2:3], exec
	s_cselect_b32 s21, s27, s35
	s_cselect_b32 s29, s26, s34
	s_add_u32 s30, s30, 0xc000
	s_addc_u32 s31, s31, 0
	s_add_u32 s57, s34, 0x10000
	v_mov_b32_e32 v2, 0
	s_addc_u32 s58, s35, 0
	s_mov_b32 s59, -2
	v_mov_b32_e32 v3, v2
	v_mov_b32_e32 v4, v2
	v_mov_b32_e32 v5, v2
	v_mov_b32_e32 v6, v2
	v_mov_b32_e32 v7, v2
	v_mov_b32_e32 v8, v2
	v_mov_b32_e32 v9, v2
	v_mov_b32_e32 v10, v2
	v_mov_b32_e32 v11, v2
	v_mov_b32_e32 v12, v2
	v_mov_b32_e32 v13, v2
	v_mov_b32_e32 v18, v2
	v_mov_b32_e32 v19, v2
	v_mov_b32_e32 v20, v2
	v_mov_b32_e32 v21, v2
	v_mov_b32_e32 v26, v2
	v_mov_b32_e32 v27, v2
	v_mov_b32_e32 v28, v2
	v_mov_b32_e32 v29, v2
	v_mov_b32_e32 v34, v2
	v_mov_b32_e32 v35, v2
	v_mov_b32_e32 v36, v2
	v_mov_b32_e32 v37, v2
	v_mov_b32_e32 v42, v2
	v_mov_b32_e32 v43, v2
	v_mov_b32_e32 v44, v2
	v_mov_b32_e32 v45, v2
	v_mov_b32_e32 v50, v2
	v_mov_b32_e32 v51, v2
	v_mov_b32_e32 v52, v2
	v_mov_b32_e32 v53, v2
	v_mov_b32_e32 v14, v2
	v_mov_b32_e32 v15, v2
	v_mov_b32_e32 v16, v2
	v_mov_b32_e32 v17, v2
	v_mov_b32_e32 v22, v2
	v_mov_b32_e32 v23, v2
	v_mov_b32_e32 v24, v2
	v_mov_b32_e32 v25, v2
	v_mov_b32_e32 v30, v2
	v_mov_b32_e32 v31, v2
	v_mov_b32_e32 v32, v2
	v_mov_b32_e32 v33, v2
	v_mov_b32_e32 v38, v2
	v_mov_b32_e32 v39, v2
	v_mov_b32_e32 v40, v2
	v_mov_b32_e32 v41, v2
	v_mov_b32_e32 v46, v2
	v_mov_b32_e32 v47, v2
	v_mov_b32_e32 v48, v2
	v_mov_b32_e32 v49, v2
	v_mov_b32_e32 v54, v2
	v_mov_b32_e32 v55, v2
	v_mov_b32_e32 v56, v2
	v_mov_b32_e32 v57, v2
	v_mov_b32_e32 v58, v2
	v_mov_b32_e32 v59, v2
	v_mov_b32_e32 v60, v2
	v_mov_b32_e32 v61, v2
	v_mov_b32_e32 v62, v2
	v_mov_b32_e32 v63, v2
	v_mov_b32_e32 v64, v2
	v_mov_b32_e32 v65, v2
	v_mov_b32_e32 v66, v2
	v_mov_b32_e32 v67, v2
	v_mov_b32_e32 v68, v2
	v_mov_b32_e32 v69, v2
	v_mov_b32_e32 v70, v2
	v_mov_b32_e32 v71, v2
	v_mov_b32_e32 v72, v2
	v_mov_b32_e32 v73, v2
	v_mov_b32_e32 v74, v2
	v_mov_b32_e32 v75, v2
	v_mov_b32_e32 v76, v2
	v_mov_b32_e32 v77, v2
	v_mov_b32_e32 v82, v2
	v_mov_b32_e32 v83, v2
	v_mov_b32_e32 v84, v2
	v_mov_b32_e32 v85, v2
	v_mov_b32_e32 v90, v2
	v_mov_b32_e32 v91, v2
	v_mov_b32_e32 v92, v2
	v_mov_b32_e32 v93, v2
	v_mov_b32_e32 v98, v2
	v_mov_b32_e32 v99, v2
	v_mov_b32_e32 v100, v2
	v_mov_b32_e32 v101, v2
	v_mov_b32_e32 v106, v2
	v_mov_b32_e32 v107, v2
	v_mov_b32_e32 v108, v2
	v_mov_b32_e32 v109, v2
	v_mov_b32_e32 v114, v2
	v_mov_b32_e32 v115, v2
	v_mov_b32_e32 v116, v2
	v_mov_b32_e32 v117, v2
	v_mov_b32_e32 v78, v2
	v_mov_b32_e32 v79, v2
	v_mov_b32_e32 v80, v2
	v_mov_b32_e32 v81, v2
	v_mov_b32_e32 v86, v2
	v_mov_b32_e32 v87, v2
	v_mov_b32_e32 v88, v2
	v_mov_b32_e32 v89, v2
	v_mov_b32_e32 v94, v2
	v_mov_b32_e32 v95, v2
	v_mov_b32_e32 v96, v2
	v_mov_b32_e32 v97, v2
	v_mov_b32_e32 v102, v2
	v_mov_b32_e32 v103, v2
	v_mov_b32_e32 v104, v2
	v_mov_b32_e32 v105, v2
	v_mov_b32_e32 v110, v2
	v_mov_b32_e32 v111, v2
	v_mov_b32_e32 v112, v2
	v_mov_b32_e32 v113, v2
	v_mov_b32_e32 v118, v2
	v_mov_b32_e32 v119, v2
	v_mov_b32_e32 v120, v2
	v_mov_b32_e32 v121, v2
	v_mov_b32_e32 v122, v2
	v_mov_b32_e32 v123, v2
	v_mov_b32_e32 v124, v2
	v_mov_b32_e32 v125, v2
	v_mov_b32_e32 v126, v2
	v_mov_b32_e32 v127, v2
	v_mov_b32_e32 v128, v2
	v_mov_b32_e32 v129, v2
	.p2alignl 6, 3212836864

; template <class Epi, class Sched, bool I8 = false>
; __device__ __forceinline__ void gemm_phase(LAS unsigned char* lds, const Gemm g, const Sched& S, const Epi& E) {
;     ...
;         for (int t = 0; t < nt; t += 2) {
;             const bool last = (t == nt - 2);
;             const char* a1 = cA + (size_t)(t + 1) * kstep;
;             const char* a2 = last ? nA : cA + (size_t)(t + 2) * kstep; const char* b2 = last ? nB : cB + (size_t)(t + 2) * kstep;
;             const char* a3 = a2 + kstep; const char* b3 = b2 + kstep;
;     __device__ __forceinline__ void operator()(const i32x4 (&acc)[2][2][4][2], const pg8::Unit& u, int wr, int wc, int fr, int fq) const {
;     ...
;             for (int mh = 0; mh < 2; ++mh) {
;                 f32x4 pa[2][2], pb[2][2]; float rs[2];
; #pragma unroll
;                 for (int mm = 0; mm < 2; ++mm) { const int row = row0 + ai * 128 + (2 * mh + mm) * 16; rs[mm] = sh[row] * alpha;
; #pragma unroll
;                     for (int bj = 0; bj < 2; ++bj) { const size_t off = (size_t)row * DM + col0 + bj * 128; pa[mm][bj] = *(const f32x4*)(res + off); pb[mm][bj] = *(const f32x4*)(res + off + 4); } }
.LBB0_4167:
	s_add_u32 s20, s20, 0xc000
	s_addc_u32 s21, s21, 0
	s_add_u32 s49, s22, 0x10000
	v_mov_b32_e32 v2, 0
	s_addc_u32 s50, s23, 0
	s_mov_b32 s51, -2
	s_waitcnt lgkmcnt(0)
	v_mov_b32_e32 v3, v2
	v_mov_b32_e32 v4, v2
	v_mov_b32_e32 v5, v2
	v_mov_b32_e32 v6, v2
	v_mov_b32_e32 v7, v2
	v_mov_b32_e32 v8, v2
	v_mov_b32_e32 v9, v2
	v_mov_b32_e32 v18, v2
	v_mov_b32_e32 v19, v2
	v_mov_b32_e32 v20, v2
	v_mov_b32_e32 v21, v2
	v_mov_b32_e32 v22, v2
	v_mov_b32_e32 v23, v2
	v_mov_b32_e32 v24, v2
	v_mov_b32_e32 v25, v2
	v_mov_b32_e32 v34, v2
	v_mov_b32_e32 v35, v2
	v_mov_b32_e32 v36, v2
	v_mov_b32_e32 v37, v2
	v_mov_b32_e32 v38, v2
	v_mov_b32_e32 v39, v2
	v_mov_b32_e32 v40, v2
	v_mov_b32_e32 v41, v2
	v_mov_b32_e32 v50, v2
	v_mov_b32_e32 v51, v2
	v_mov_b32_e32 v52, v2
	v_mov_b32_e32 v53, v2
	v_mov_b32_e32 v54, v2
	v_mov_b32_e32 v55, v2
	v_mov_b32_e32 v56, v2
	v_mov_b32_e32 v57, v2
	v_mov_b32_e32 v10, v2
	v_mov_b32_e32 v11, v2
	v_mov_b32_e32 v12, v2
	v_mov_b32_e32 v13, v2
	v_mov_b32_e32 v14, v2
	v_mov_b32_e32 v15, v2
	v_mov_b32_e32 v16, v2
	v_mov_b32_e32 v17, v2
	v_mov_b32_e32 v26, v2
	v_mov_b32_e32 v27, v2
	v_mov_b32_e32 v28, v2
	v_mov_b32_e32 v29, v2
	v_mov_b32_e32 v30, v2
	v_mov_b32_e32 v31, v2
	v_mov_b32_e32 v32, v2
	v_mov_b32_e32 v33, v2
	v_mov_b32_e32 v42, v2
	v_mov_b32_e32 v43, v2
	v_mov_b32_e32 v44, v2
	v_mov_b32_e32 v45, v2
	v_mov_b32_e32 v46, v2
	v_mov_b32_e32 v47, v2
	v_mov_b32_e32 v48, v2
	v_mov_b32_e32 v49, v2
	v_mov_b32_e32 v58, v2
	v_mov_b32_e32 v59, v2
	v_mov_b32_e32 v60, v2
	v_mov_b32_e32 v61, v2
	v_mov_b32_e32 v62, v2
	v_mov_b32_e32 v63, v2
	v_mov_b32_e32 v64, v2
	v_mov_b32_e32 v65, v2
	v_mov_b32_e32 v82, v2
	v_mov_b32_e32 v83, v2
	v_mov_b32_e32 v84, v2
	v_mov_b32_e32 v85, v2
	v_mov_b32_e32 v86, v2
	v_mov_b32_e32 v87, v2
	v_mov_b32_e32 v88, v2
	v_mov_b32_e32 v89, v2
	v_mov_b32_e32 v98, v2
	v_mov_b32_e32 v99, v2
	v_mov_b32_e32 v100, v2
	v_mov_b32_e32 v101, v2
	v_mov_b32_e32 v102, v2
	v_mov_b32_e32 v103, v2
	v_mov_b32_e32 v104, v2
	v_mov_b32_e32 v105, v2
	v_mov_b32_e32 v114, v2
	v_mov_b32_e32 v115, v2
	v_mov_b32_e32 v116, v2
	v_mov_b32_e32 v117, v2
	v_mov_b32_e32 v118, v2
	v_mov_b32_e32 v119, v2
	v_mov_b32_e32 v120, v2
	v_mov_b32_e32 v121, v2
	v_mov_b32_e32 v130, v2
	v_mov_b32_e32 v131, v2
	v_mov_b32_e32 v132, v2
	v_mov_b32_e32 v133, v2
	v_mov_b32_e32 v134, v2
	v_mov_b32_e32 v135, v2
	v_mov_b32_e32 v136, v2
	v_mov_b32_e32 v137, v2
	v_mov_b32_e32 v90, v2
	v_mov_b32_e32 v91, v2
	v_mov_b32_e32 v92, v2
	v_mov_b32_e32 v93, v2
	v_mov_b32_e32 v94, v2
	v_mov_b32_e32 v95, v2
	v_mov_b32_e32 v96, v2
	v_mov_b32_e32 v97, v2
	v_mov_b32_e32 v106, v2
	v_mov_b32_e32 v107, v2
	v_mov_b32_e32 v108, v2
	v_mov_b32_e32 v109, v2
	v_mov_b32_e32 v110, v2
	v_mov_b32_e32 v111, v2
	v_mov_b32_e32 v112, v2
	v_mov_b32_e32 v113, v2
	v_mov_b32_e32 v122, v2
	v_mov_b32_e32 v123, v2
	v_mov_b32_e32 v124, v2
	v_mov_b32_e32 v125, v2
	v_mov_b32_e32 v126, v2
	v_mov_b32_e32 v127, v2
	v_mov_b32_e32 v128, v2
	v_mov_b32_e32 v129, v2
	v_mov_b32_e32 v138, v2
	v_mov_b32_e32 v139, v2
	v_mov_b32_e32 v140, v2
	v_mov_b32_e32 v141, v2
	v_mov_b32_e32 v142, v2
	v_mov_b32_e32 v143, v2
	v_mov_b32_e32 v144, v2
	v_mov_b32_e32 v145, v2
	v_lshl_add_u32 v252, s47, 8, v1
	v_lshl_or_b32 v253, s48, 8, v177
	v_lshlrev_b32_e32 v252, 14, v252
	v_lshl_add_u32 v252, v253, 2, v252
	v_mov_b32_e32 v253, 0
	v_lshl_add_u64 v[252:253], v[252:253], 0, s[76:77]
	v_mov_b32_e32 v248, 0x40000
	v_mov_b32_e32 v249, 0
	v_lshl_add_u64 v[248:249], v[248:249], 0, v[252:253]
	global_load_dwordx4 v[222:225], v[252:253], off nt
	global_load_dwordx4 v[226:229], v[252:253], off offset:16 nt
	global_load_dwordx4 v[230:233], v[252:253], off offset:512 nt
	global_load_dwordx4 v[234:237], v[248:249], off offset:16 nt
	global_load_dwordx4 v[238:241], v[248:249], off nt
	global_load_dwordx4 v[242:245], v[248:249], off offset:528 nt
	s_nop 0
	global_load_dwordx4 v[252:255], v[252:253], off offset:528 nt
	s_nop 0
	global_load_dwordx4 v[248:251], v[248:249], off offset:512 nt
	.p2alignl 6, 3212836864
